# st3 item split in a group: ssd_z + 1 rowfin for blocks 0-3, 3 rowfin for blocks 4-7 (was ssd_z + 2 vs 2)
# speedup vs baseline: 1.0089x; 1.0045x over previous
.LBB0_798:
	s_andn2_b64 vcc, exec, s[2:3]
	s_cbranch_vccnz .LBB0_1364
	v_readlane_b32 s0, v255, 46
	s_cmp_lt_i32 s0, 2
	s_mov_b64 s[2:3], -1
	s_cbranch_scc1 .LBB0_873
	v_readlane_b32 s0, v255, 46
	s_cmp_gt_i32 s0, 2
	s_cbranch_scc0 .LBB0_809
	s_cmpk_gt_i32 s45, 0x4ff
	s_mov_b32 s29, 0x6bb9000
	s_cbranch_scc1 .LBB0_808
	s_add_u32 s4, s82, 0xa3b9000
	s_addc_u32 s5, s83, 0
	s_add_u32 s6, s82, 0xe3b9000
	s_addc_u32 s7, s83, 0
	s_add_u32 s8, s82, 0x10bb9000
	s_addc_u32 s9, s83, 0
	s_add_u32 s10, s82, 0x113b9000
	s_addc_u32 s11, s83, 0
	s_add_u32 s12, s82, 0x6a31000
	s_addc_u32 s13, s83, 0
	s_add_u32 s14, s82, 0x103b9000
	s_addc_u32 s15, s83, 0
	s_add_u32 s16, s82, 0x69b0000
	s_addc_u32 s17, s83, 0
	s_and_b32 s0, s45, 1
	s_lshl_b32 s1, s0, 7
	s_add_u32 s2, s82, s1
	s_addc_u32 s3, s83, 0
	s_add_u32 s18, s2, 0x107b9000
	s_addc_u32 s19, s3, 0
	s_lshl_b32 s22, s0, 1
	s_lshl_b32 s0, s0, 8
	s_add_u32 s0, s82, s0
	s_addc_u32 s2, s83, 0
	s_add_u32 s20, s0, 0xf3b9000
	s_addc_u32 s21, s2, 0
	s_lshl_b32 s0, s45, 4
	s_or_b32 s23, s22, 1
	s_add_i32 s27, s0, 0xfffff000
	s_lshl_b32 s30, s78, 5
	s_lshl_b32 s52, s1, 1
	s_mov_b32 s31, s45
	s_cmpk_lg_u32 s80, 0x200
	s_cbranch_scc1 .Lst3_i_done
	s_lshr_b32 s33, s45, 1
	s_and_b32 s34, s33, 7
	s_lshl_b32 s34, s34, 3
	s_lshr_b32 s35, s33, 5
	s_add_i32 s34, s34, s35
	s_bfe_u32 s35, s33, 0x20003
	s_lshl_b32 s35, s35, 1
	s_and_b32 s33, s45, 1
	s_add_i32 s35, s35, s33
	s_lshl_b32 s32, s34, 4
	s_addk_i32 s32, 0x100
	s_mul_i32 s33, s35, 3
	s_add_i32 s33, s33, -8
	s_cmp_lt_u32 s35, 4
	s_cselect_b32 s33, s35, s33
	s_cselect_b32 s27, 0, 2
	s_add_i32 s32, s32, s33
	s_add_i32 s33, s32, s27
	s_lshl_b32 s34, s34, 2
	s_add_i32 s31, s34, s35
	s_cmp_lt_u32 s35, 4
	s_cselect_b32 s31, s31, s32
	s_lshl_b32 s27, s31, 4
	s_add_i32 s27, s27, 0xfffff000

.LBB0_803:
	s_cmpk_lg_u32 s80, 0x200
	s_cbranch_scc1 .Lst3_gen
	s_cmpk_lt_u32 s31, 0x100
	s_cbranch_scc1 .Lst3_first
	s_cmp_eq_u32 s31, s33
	s_cbranch_scc1 .LBB0_808
	s_add_i32 s31, s31, 1
	s_branch .Lst3_set
